# combo4 + FINAL and NORM row loops: loop-top store-drain waits removed (rows of different trips are disjoint; later counted waits unchanged)
# baseline (speedup 1.0000x reference)
.LBB0_204:
	v_ashrrev_i32_e32 v18, 11, v156
	v_mul_hi_i32_i24_e32 v19, 0x3000, v18
	v_mul_i32_i24_e32 v18, 0x3000, v18
	v_lshl_add_u64 v[18:19], s[34:35], 0, v[18:19]
	v_lshl_add_u64 v[18:19], v[18:19], 0, v[0:1]
	s_mov_b64 s[8:9], 0x1000
	s_movk_i32 s3, 0x1000
	v_lshl_add_u64 v[20:21], v[18:19], 0, s[8:9]
	v_add_co_u32_e32 v18, vcc, s3, v18
	v_add_u32_e32 v24, s5, v156
	s_nop 0
	v_addc_co_u32_e32 v19, vcc, 0, v19, vcc
	global_load_dwordx4 v[138:141], v[160:161], off offset:-2048
	global_load_dwordx4 v[130:133], v[160:161], off offset:-1024
	global_load_dwordx4 v[134:137], v[20:21], off offset:1024
	global_load_dwordx4 v[122:125], v[20:21], off offset:2048
	global_load_dwordx4 v[126:129], v[160:161], off
	global_load_dwordx4 v[118:121], v[160:161], off offset:1024
	global_load_dwordx4 v[142:145], v[18:19], off
	global_load_dwordx4 v[114:117], v[20:21], off offset:3072
	s_movk_i32 s2, 0x4000
	v_cmp_gt_i32_e64 s[44:45], s2, v24
	s_nop 1
	v_cndmask_b32_e64 v18, v156, v24, s[44:45]
	v_ashrrev_i32_e32 v19, 31, v18
	v_lshlrev_b64 v[20:21], 12, v[18:19]
	v_ashrrev_i32_e32 v18, 11, v18
	v_mul_hi_i32_i24_e32 v19, 0x3000, v18
	v_mul_i32_i24_e32 v18, 0x3000, v18
	v_lshl_add_u64 v[18:19], s[34:35], 0, v[18:19]
	v_lshl_add_u64 v[18:19], v[18:19], 0, v[0:1]
	v_add_u32_e32 v24, s5, v24
	v_lshl_add_u64 v[20:21], v[148:149], 0, v[20:21]
	v_lshl_add_u64 v[22:23], v[18:19], 0, s[8:9]
	v_add_co_u32_e32 v18, vcc, s3, v18
	v_cmp_gt_i32_e64 s[42:43], s2, v24
	s_nop 0
	v_addc_co_u32_e32 v19, vcc, 0, v19, vcc
	global_load_dwordx4 v[106:109], v[20:21], off
	global_load_dwordx4 v[102:105], v[20:21], off offset:1024
	global_load_dwordx4 v[98:101], v[22:23], off offset:1024
	global_load_dwordx4 v[90:93], v[22:23], off offset:2048
	global_load_dwordx4 v[94:97], v[20:21], off offset:2048
	global_load_dwordx4 v[86:89], v[20:21], off offset:3072
	global_load_dwordx4 v[110:113], v[18:19], off
	global_load_dwordx4 v[82:85], v[22:23], off offset:3072
	v_cndmask_b32_e64 v18, v156, v24, s[42:43]
	v_ashrrev_i32_e32 v19, 31, v18
	v_lshlrev_b64 v[20:21], 12, v[18:19]
	v_ashrrev_i32_e32 v18, 11, v18
	v_mul_hi_i32_i24_e32 v19, 0x3000, v18
	v_mul_i32_i24_e32 v18, 0x3000, v18
	v_lshl_add_u64 v[18:19], s[34:35], 0, v[18:19]
	v_lshl_add_u64 v[18:19], v[18:19], 0, v[0:1]
	v_add_u32_e32 v157, s5, v24
	v_lshl_add_u64 v[20:21], v[148:149], 0, v[20:21]
	v_lshl_add_u64 v[22:23], v[18:19], 0, s[8:9]
	v_add_co_u32_e32 v18, vcc, s3, v18
	v_cmp_gt_i32_e64 s[40:41], s2, v157
	s_nop 0
	v_addc_co_u32_e32 v19, vcc, 0, v19, vcc
	global_load_dwordx4 v[74:77], v[20:21], off
	global_load_dwordx4 v[70:73], v[20:21], off offset:1024
	global_load_dwordx4 v[66:69], v[22:23], off offset:1024
	global_load_dwordx4 v[58:61], v[22:23], off offset:2048
	global_load_dwordx4 v[62:65], v[20:21], off offset:2048
	global_load_dwordx4 v[54:57], v[20:21], off offset:3072
	global_load_dwordx4 v[78:81], v[18:19], off
	s_waitcnt lgkmcnt(0)
	global_load_dwordx4 v[50:53], v[22:23], off offset:3072
	v_cndmask_b32_e64 v18, v156, v157, s[40:41]
	v_ashrrev_i32_e32 v19, 31, v18
	v_lshlrev_b64 v[20:21], 12, v[18:19]
	v_ashrrev_i32_e32 v18, 11, v18
	v_mul_hi_i32_i24_e32 v19, 0x3000, v18
	v_mul_i32_i24_e32 v18, 0x3000, v18
	v_lshl_add_u64 v[18:19], s[34:35], 0, v[18:19]
	v_lshl_add_u64 v[18:19], v[18:19], 0, v[0:1]
	v_lshl_add_u64 v[168:169], v[18:19], 0, s[8:9]
	v_add_co_u32_e32 v18, vcc, s3, v18
	v_lshl_add_u64 v[20:21], v[148:149], 0, v[20:21]
	s_nop 0
	v_addc_co_u32_e32 v19, vcc, 0, v19, vcc
	global_load_dwordx4 v[42:45], v[20:21], off
	global_load_dwordx4 v[38:41], v[20:21], off offset:1024
	global_load_dwordx4 v[34:37], v[168:169], off offset:1024
	global_load_dwordx4 v[26:29], v[168:169], off offset:2048
	global_load_dwordx4 v[30:33], v[20:21], off offset:2048
	global_load_dwordx4 v[22:25], v[20:21], off offset:3072
	global_load_dwordx4 v[46:49], v[18:19], off
	s_nop 0
	global_load_dwordx4 v[18:21], v[168:169], off offset:3072
	s_waitcnt vmcnt(31)
	v_mul_f32_e32 v168, v139, v139
	s_waitcnt vmcnt(30)
	v_mul_f32_e32 v169, v131, v131
	v_fmac_f32_e32 v168, v138, v138
	v_fmac_f32_e32 v169, v130, v130
	v_fmac_f32_e32 v168, v140, v140
	v_fmac_f32_e32 v169, v132, v132
	v_fmac_f32_e32 v168, v141, v141
	v_fmac_f32_e32 v169, v133, v133
	v_add_f32_e32 v168, v168, v169
	s_waitcnt vmcnt(27)
	v_mul_f32_e32 v169, v127, v127
	v_fmac_f32_e32 v169, v126, v126
	v_fmac_f32_e32 v169, v128, v128
	v_fmac_f32_e32 v169, v129, v129
	v_add_f32_e32 v168, v168, v169
	s_waitcnt vmcnt(26)
	v_mul_f32_e32 v169, v119, v119
	v_fmac_f32_e32 v169, v118, v118
	v_fmac_f32_e32 v169, v120, v120
	v_fmac_f32_e32 v169, v121, v121
	v_add_f32_e32 v168, v168, v169
	ds_bpermute_b32 v169, v162, v168
	s_waitcnt lgkmcnt(0)
	v_add_f32_e32 v168, v168, v169
	ds_bpermute_b32 v169, v163, v168
	s_waitcnt lgkmcnt(0)
	v_add_f32_e32 v168, v168, v169
	ds_bpermute_b32 v169, v164, v168
	s_waitcnt lgkmcnt(0)
	v_add_f32_e32 v168, v168, v169
	ds_bpermute_b32 v169, v165, v168
	s_waitcnt lgkmcnt(0)
	v_add_f32_e32 v168, v168, v169
	ds_bpermute_b32 v169, v166, v168
	s_waitcnt lgkmcnt(0)
	v_add_f32_e32 v168, v168, v169
	ds_bpermute_b32 v169, v167, v168
	s_and_saveexec_b64 s[2:3], s[38:39]
	s_cbranch_execz .LBB0_206
	s_waitcnt lgkmcnt(0)
	v_add_f32_e32 v170, v168, v169
	v_lshl_add_u64 v[168:169], s[18:19], 0, v[154:155]
	global_store_dword v[168:169], v170, off

.LBB0_1251:
	v_add_u32_e32 v16, s17, v78
	v_cmp_gt_i32_e64 s[2:3], s16, v16
	v_add_u32_e32 v76, s11, v78
	v_cmp_gt_i32_e64 s[0:1], s16, v76
	v_cndmask_b32_e64 v16, v78, v16, s[2:3]
	v_ashrrev_i32_e32 v17, 31, v16
	v_lshlrev_b64 v[18:19], 12, v[16:17]
	v_lshl_add_u64 v[18:19], v[66:67], 0, v[18:19]
	global_load_dwordx4 v[60:63], v[18:19], off
	global_load_dwordx4 v[56:59], v[18:19], off offset:1024
	global_load_dwordx4 v[48:51], v[18:19], off offset:2048
	global_load_dwordx4 v[36:39], v[18:19], off offset:3072
	v_lshl_add_u64 v[16:17], v[16:17], 2, s[8:9]
	global_load_dword v81, v[70:71], off
	global_load_dword v80, v[16:17], off
	v_cndmask_b32_e64 v16, v78, v76, s[0:1]
	v_ashrrev_i32_e32 v17, 31, v16
	v_add_u32_e32 v74, s18, v78
	v_lshlrev_b64 v[18:19], 12, v[16:17]
	v_lshl_add_u64 v[98:99], v[68:69], 0, v[64:65]
	v_lshl_add_u64 v[16:17], v[16:17], 2, s[8:9]
	v_cmp_gt_i32_e32 vcc, s16, v74
	v_lshl_add_u64 v[18:19], v[66:67], 0, v[18:19]
	global_load_dwordx4 v[82:85], v[98:99], off offset:1024
	global_load_dwordx4 v[86:89], v[98:99], off
	global_load_dwordx4 v[52:55], v[18:19], off
	global_load_dwordx4 v[44:47], v[18:19], off offset:1024
	global_load_dwordx4 v[90:93], v[98:99], off offset:3072
	global_load_dwordx4 v[94:97], v[98:99], off offset:2048
	global_load_dwordx4 v[40:43], v[18:19], off offset:2048
	global_load_dwordx4 v[32:35], v[18:19], off offset:3072
	global_load_dword v77, v[16:17], off
	v_cndmask_b32_e32 v16, v78, v74, vcc
	v_ashrrev_i32_e32 v17, 31, v16
	v_lshlrev_b64 v[18:19], 12, v[16:17]
	v_lshl_add_u64 v[100:101], v[66:67], 0, v[18:19]
	v_lshl_add_u64 v[102:103], v[16:17], 2, s[8:9]
	global_load_dwordx4 v[28:31], v[100:101], off
	global_load_dwordx4 v[24:27], v[100:101], off offset:1024
	global_load_dword v75, v[102:103], off
	global_load_dwordx4 v[20:23], v[100:101], off offset:2048
	global_load_dwordx4 v[16:19], v[100:101], off offset:3072
	s_waitcnt vmcnt(15)
	v_fmamk_f32 v81, v81, 0x3a800000, v79
	v_mul_f32_e32 v100, 0x4b800000, v81
	v_cmp_gt_f32_e64 s[4:5], s19, v81
	s_nop 1
	v_cndmask_b32_e64 v81, v81, v100, s[4:5]
	v_rsq_f32_e32 v81, v81
	s_nop 0
	v_mul_f32_e32 v100, 0x45800000, v81
	v_cndmask_b32_e64 v100, v81, v100, s[4:5]
	s_waitcnt vmcnt(12)
	v_pk_mul_f32 v[86:87], v[86:87], v[100:101] op_sel_hi:[1,0]
	v_pk_mul_f32 v[88:89], v[88:89], v[100:101] op_sel_hi:[1,0]
	v_pk_mul_f32 v[102:103], v[82:83], v[100:101] op_sel_hi:[1,0]
	v_pk_mul_f32 v[104:105], v[84:85], v[100:101] op_sel_hi:[1,0]
	s_waitcnt vmcnt(8)
	v_pk_mul_f32 v[94:95], v[94:95], v[100:101] op_sel_hi:[1,0]
	v_pk_mul_f32 v[96:97], v[96:97], v[100:101] op_sel_hi:[1,0]
	v_pk_mul_f32 v[106:107], v[90:91], v[100:101] op_sel_hi:[1,0]
	v_pk_mul_f32 v[100:101], v[92:93], v[100:101] op_sel_hi:[1,0]
	v_pk_mul_f32 v[84:85], v[2:3], v[88:89]
	v_pk_mul_f32 v[82:83], v[0:1], v[86:87]
	v_pk_mul_f32 v[88:89], v[6:7], v[104:105]
	v_pk_mul_f32 v[86:87], v[4:5], v[102:103]
	v_pk_mul_f32 v[92:93], v[10:11], v[96:97]
	v_pk_mul_f32 v[90:91], v[8:9], v[94:95]
	v_pk_mul_f32 v[96:97], v[14:15], v[100:101]
	v_pk_mul_f32 v[94:95], v[12:13], v[106:107]
	global_store_dwordx4 v[98:99], v[82:85], off
	global_store_dwordx4 v[98:99], v[86:89], off offset:1024
	global_store_dwordx4 v[98:99], v[90:93], off offset:2048
	global_store_dwordx4 v[98:99], v[94:97], off offset:3072
	s_and_saveexec_b64 s[4:5], s[2:3]
	s_cbranch_execz .LBB0_1254
	v_fmamk_f32 v80, v80, 0x3a800000, v79
	v_mul_f32_e32 v81, 0x4b800000, v80
	v_cmp_gt_f32_e64 s[2:3], s19, v80
	v_lshl_add_u64 v[82:83], v[72:73], 0, v[64:65]
	s_nop 0
	v_cndmask_b32_e64 v80, v80, v81, s[2:3]
	v_rsq_f32_e32 v80, v80
	s_nop 0
	v_mul_f32_e32 v81, 0x45800000, v80
	v_cndmask_b32_e64 v80, v80, v81, s[2:3]
	v_pk_mul_f32 v[60:61], v[60:61], v[80:81] op_sel_hi:[1,0]
	v_pk_mul_f32 v[62:63], v[62:63], v[80:81] op_sel_hi:[1,0]
	v_pk_mul_f32 v[56:57], v[56:57], v[80:81] op_sel_hi:[1,0]
	v_pk_mul_f32 v[58:59], v[58:59], v[80:81] op_sel_hi:[1,0]
	v_pk_mul_f32 v[48:49], v[48:49], v[80:81] op_sel_hi:[1,0]
	v_pk_mul_f32 v[50:51], v[50:51], v[80:81] op_sel_hi:[1,0]
	v_pk_mul_f32 v[36:37], v[36:37], v[80:81] op_sel_hi:[1,0]
	v_pk_mul_f32 v[38:39], v[38:39], v[80:81] op_sel_hi:[1,0]
	v_pk_mul_f32 v[62:63], v[2:3], v[62:63]
	v_pk_mul_f32 v[60:61], v[0:1], v[60:61]
	v_pk_mul_f32 v[58:59], v[6:7], v[58:59]
	v_pk_mul_f32 v[56:57], v[4:5], v[56:57]
	v_pk_mul_f32 v[50:51], v[10:11], v[50:51]
	v_pk_mul_f32 v[48:49], v[8:9], v[48:49]
	v_pk_mul_f32 v[38:39], v[14:15], v[38:39]
	v_pk_mul_f32 v[36:37], v[12:13], v[36:37]
	global_store_dwordx4 v[82:83], v[60:63], off
	global_store_dwordx4 v[82:83], v[56:59], off offset:1024
	global_store_dwordx4 v[82:83], v[48:51], off offset:2048
	global_store_dwordx4 v[82:83], v[36:39], off offset:3072
	s_or_b64 exec, exec, s[4:5]
	s_and_saveexec_b64 s[2:3], s[0:1]
	s_cbranch_execnz .LBB0_1255
